# P1 gate epilogue: packed f32 fma/add for the sigmoid affine steps
# speedup vs baseline: 1.0012x; 1.0012x over previous
.LBB0_138:
	s_cmp_gt_u32 s94, 7
	s_cbranch_scc0 .LBB0_140
	v_ashrrev_i32_e32 v141, 31, v140
	s_lshl_b32 s12, s94, 8
	s_addk_i32 s12, 0xf800
	v_lshl_add_u64 v[142:143], s[12:13], 2, v[134:135]
	global_load_dwordx4 v[186:189], v[142:143], off
	global_load_dwordx4 v[190:193], v[142:143], off offset:16
	global_load_dwordx4 v[194:197], v[142:143], off offset:32
	global_load_dwordx4 v[198:201], v[142:143], off offset:48
	v_lshlrev_b32_e32 v185, 2, v140
	global_load_dword v202, v185, s[18:19]
	global_load_dword v203, v185, s[18:19] offset:64
	global_load_dword v204, v185, s[18:19] offset:128
	global_load_dword v205, v185, s[18:19] offset:192
	global_load_dword v206, v185, s[18:19] offset:512
	global_load_dword v207, v185, s[18:19] offset:576
	global_load_dword v208, v185, s[18:19] offset:640
	global_load_dword v209, v185, s[18:19] offset:704
	v_lshl_add_u64 v[148:149], v[132:133], 0, s[12:13]
	v_lshlrev_b64 v[146:147], 11, v[140:141]
	v_lshl_add_u64 v[148:149], v[148:149], 0, v[146:147]
	s_mov_b64 s[54:55], 0
	v_mov_b32_e32 v226, 1.0
	v_mov_b32_e32 v227, 1.0
	v_mov_b32_e32 v228, 0x437f0000
	v_mov_b32_e32 v229, 0x437f0000
	v_mov_b32_e32 v230, 0.5
	v_mov_b32_e32 v231, 0.5
	s_waitcnt vmcnt(8)
	v_mul_f32_e32 v186, 0xbfb8aa3b, v186
	v_mul_f32_e32 v187, 0xbfb8aa3b, v187
	v_mul_f32_e32 v188, 0xbfb8aa3b, v188
	v_mul_f32_e32 v189, 0xbfb8aa3b, v189
	v_mul_f32_e32 v190, 0xbfb8aa3b, v190
	v_mul_f32_e32 v191, 0xbfb8aa3b, v191
	v_mul_f32_e32 v192, 0xbfb8aa3b, v192
	v_mul_f32_e32 v193, 0xbfb8aa3b, v193
	v_mul_f32_e32 v194, 0xbfb8aa3b, v194
	v_mul_f32_e32 v195, 0xbfb8aa3b, v195
	v_mul_f32_e32 v196, 0xbfb8aa3b, v196
	v_mul_f32_e32 v197, 0xbfb8aa3b, v197
	v_mul_f32_e32 v198, 0xbfb8aa3b, v198
	v_mul_f32_e32 v199, 0xbfb8aa3b, v199
	v_mul_f32_e32 v200, 0xbfb8aa3b, v200
	v_mul_f32_e32 v201, 0xbfb8aa3b, v201
	s_waitcnt vmcnt(7)
	v_mul_f32_e32 v130, 0xbfb8aa3b, v202
	v_pk_fma_f32 v[210:211], v[124:125], v[130:131], v[186:187] op_sel_hi:[1,0,1]
	v_pk_fma_f32 v[212:213], v[126:127], v[130:131], v[188:189] op_sel_hi:[1,0,1]
	v_pk_fma_f32 v[214:215], v[120:121], v[130:131], v[190:191] op_sel_hi:[1,0,1]
	v_pk_fma_f32 v[216:217], v[122:123], v[130:131], v[192:193] op_sel_hi:[1,0,1]
	v_pk_fma_f32 v[218:219], v[116:117], v[130:131], v[194:195] op_sel_hi:[1,0,1]
	v_pk_fma_f32 v[220:221], v[118:119], v[130:131], v[196:197] op_sel_hi:[1,0,1]
	v_pk_fma_f32 v[222:223], v[112:113], v[130:131], v[198:199] op_sel_hi:[1,0,1]
	v_pk_fma_f32 v[224:225], v[114:115], v[130:131], v[200:201] op_sel_hi:[1,0,1]
	v_exp_f32_e32 v210, v210
	v_exp_f32_e32 v211, v211
	v_exp_f32_e32 v212, v212
	v_exp_f32_e32 v213, v213
	v_exp_f32_e32 v214, v214
	v_exp_f32_e32 v215, v215
	v_exp_f32_e32 v216, v216
	v_exp_f32_e32 v217, v217
	v_exp_f32_e32 v218, v218
	v_exp_f32_e32 v219, v219
	v_exp_f32_e32 v220, v220
	v_exp_f32_e32 v221, v221
	v_exp_f32_e32 v222, v222
	v_exp_f32_e32 v223, v223
	v_exp_f32_e32 v224, v224
	v_exp_f32_e32 v225, v225
	v_pk_add_f32 v[210:211], v[210:211], v[226:227]
	v_pk_add_f32 v[212:213], v[212:213], v[226:227]
	v_pk_add_f32 v[214:215], v[214:215], v[226:227]
	v_pk_add_f32 v[216:217], v[216:217], v[226:227]
	v_pk_add_f32 v[218:219], v[218:219], v[226:227]
	v_pk_add_f32 v[220:221], v[220:221], v[226:227]
	v_pk_add_f32 v[222:223], v[222:223], v[226:227]
	v_pk_add_f32 v[224:225], v[224:225], v[226:227]
	v_rcp_f32_e32 v210, v210
	v_rcp_f32_e32 v211, v211
	v_rcp_f32_e32 v212, v212
	v_rcp_f32_e32 v213, v213
	v_rcp_f32_e32 v214, v214
	v_rcp_f32_e32 v215, v215
	v_rcp_f32_e32 v216, v216
	v_rcp_f32_e32 v217, v217
	v_rcp_f32_e32 v218, v218
	v_rcp_f32_e32 v219, v219
	v_rcp_f32_e32 v220, v220
	v_rcp_f32_e32 v221, v221
	v_rcp_f32_e32 v222, v222
	v_rcp_f32_e32 v223, v223
	v_rcp_f32_e32 v224, v224
	v_rcp_f32_e32 v225, v225
	v_pk_fma_f32 v[210:211], v[210:211], v[228:229], v[230:231]
	v_pk_fma_f32 v[212:213], v[212:213], v[228:229], v[230:231]
	v_pk_fma_f32 v[214:215], v[214:215], v[228:229], v[230:231]
	v_pk_fma_f32 v[216:217], v[216:217], v[228:229], v[230:231]
	v_pk_fma_f32 v[218:219], v[218:219], v[228:229], v[230:231]
	v_pk_fma_f32 v[220:221], v[220:221], v[228:229], v[230:231]
	v_pk_fma_f32 v[222:223], v[222:223], v[228:229], v[230:231]
	v_pk_fma_f32 v[224:225], v[224:225], v[228:229], v[230:231]
	v_med3_f32 v210, v210, 1.0, v182
	v_med3_f32 v211, v211, 1.0, v182
	v_med3_f32 v212, v212, 1.0, v182
	v_med3_f32 v213, v213, 1.0, v182
	v_med3_f32 v214, v214, 1.0, v182
	v_med3_f32 v215, v215, 1.0, v182
	v_med3_f32 v216, v216, 1.0, v182
	v_med3_f32 v217, v217, 1.0, v182
	v_med3_f32 v218, v218, 1.0, v182
	v_med3_f32 v219, v219, 1.0, v182
	v_med3_f32 v220, v220, 1.0, v182
	v_med3_f32 v221, v221, 1.0, v182
	v_med3_f32 v222, v222, 1.0, v182
	v_med3_f32 v223, v223, 1.0, v182
	v_med3_f32 v224, v224, 1.0, v182
	v_med3_f32 v225, v225, 1.0, v182
	v_cvt_u32_f32_e32 v210, v210
	v_cvt_u32_f32_e32 v211, v211
	v_cvt_u32_f32_sdwa v212, v212 dst_sel:WORD_1 dst_unused:UNUSED_PAD src0_sel:DWORD
	v_cvt_u32_f32_sdwa v213, v213 dst_sel:BYTE_3 dst_unused:UNUSED_PAD src0_sel:DWORD
	v_cvt_u32_f32_e32 v214, v214
	v_cvt_u32_f32_e32 v215, v215
	v_cvt_u32_f32_sdwa v216, v216 dst_sel:WORD_1 dst_unused:UNUSED_PAD src0_sel:DWORD
	v_cvt_u32_f32_sdwa v217, v217 dst_sel:BYTE_3 dst_unused:UNUSED_PAD src0_sel:DWORD
	v_cvt_u32_f32_e32 v218, v218
	v_cvt_u32_f32_e32 v219, v219
	v_cvt_u32_f32_sdwa v220, v220 dst_sel:WORD_1 dst_unused:UNUSED_PAD src0_sel:DWORD
	v_cvt_u32_f32_sdwa v221, v221 dst_sel:BYTE_3 dst_unused:UNUSED_PAD src0_sel:DWORD
	v_cvt_u32_f32_e32 v222, v222
	v_cvt_u32_f32_e32 v223, v223
	v_cvt_u32_f32_sdwa v224, v224 dst_sel:WORD_1 dst_unused:UNUSED_PAD src0_sel:DWORD
	v_cvt_u32_f32_sdwa v225, v225 dst_sel:BYTE_3 dst_unused:UNUSED_PAD src0_sel:DWORD
	v_lshl_or_b32 v210, v211, 8, v210
	v_lshl_or_b32 v214, v215, 8, v214
	v_lshl_or_b32 v218, v219, 8, v218
	v_lshl_or_b32 v222, v223, 8, v222
	v_or3_b32 v236, v210, v212, v213
	v_or3_b32 v237, v214, v216, v217
	v_or3_b32 v238, v218, v220, v221
	v_or3_b32 v239, v222, v224, v225
	global_store_dwordx4 v[148:149], v[236:239], off nt
	s_waitcnt vmcnt(7)
	v_mul_f32_e32 v130, 0xbfb8aa3b, v203
	v_pk_fma_f32 v[210:211], v[108:109], v[130:131], v[186:187] op_sel_hi:[1,0,1]
	v_pk_fma_f32 v[212:213], v[110:111], v[130:131], v[188:189] op_sel_hi:[1,0,1]
	v_pk_fma_f32 v[214:215], v[104:105], v[130:131], v[190:191] op_sel_hi:[1,0,1]
	v_pk_fma_f32 v[216:217], v[106:107], v[130:131], v[192:193] op_sel_hi:[1,0,1]
	v_pk_fma_f32 v[218:219], v[100:101], v[130:131], v[194:195] op_sel_hi:[1,0,1]
	v_pk_fma_f32 v[220:221], v[102:103], v[130:131], v[196:197] op_sel_hi:[1,0,1]
	v_pk_fma_f32 v[222:223], v[96:97], v[130:131], v[198:199] op_sel_hi:[1,0,1]
	v_pk_fma_f32 v[224:225], v[98:99], v[130:131], v[200:201] op_sel_hi:[1,0,1]
	v_exp_f32_e32 v210, v210
	v_exp_f32_e32 v211, v211
	v_exp_f32_e32 v212, v212
	v_exp_f32_e32 v213, v213
	v_exp_f32_e32 v214, v214
	v_exp_f32_e32 v215, v215
	v_exp_f32_e32 v216, v216
	v_exp_f32_e32 v217, v217
	v_exp_f32_e32 v218, v218
	v_exp_f32_e32 v219, v219
	v_exp_f32_e32 v220, v220
	v_exp_f32_e32 v221, v221
	v_exp_f32_e32 v222, v222
	v_exp_f32_e32 v223, v223
	v_exp_f32_e32 v224, v224
	v_exp_f32_e32 v225, v225
	v_pk_add_f32 v[210:211], v[210:211], v[226:227]
	v_pk_add_f32 v[212:213], v[212:213], v[226:227]
	v_pk_add_f32 v[214:215], v[214:215], v[226:227]
	v_pk_add_f32 v[216:217], v[216:217], v[226:227]
	v_pk_add_f32 v[218:219], v[218:219], v[226:227]
	v_pk_add_f32 v[220:221], v[220:221], v[226:227]
	v_pk_add_f32 v[222:223], v[222:223], v[226:227]
	v_pk_add_f32 v[224:225], v[224:225], v[226:227]
	v_rcp_f32_e32 v210, v210
	v_rcp_f32_e32 v211, v211
	v_rcp_f32_e32 v212, v212
	v_rcp_f32_e32 v213, v213
	v_rcp_f32_e32 v214, v214
	v_rcp_f32_e32 v215, v215
	v_rcp_f32_e32 v216, v216
	v_rcp_f32_e32 v217, v217
	v_rcp_f32_e32 v218, v218
	v_rcp_f32_e32 v219, v219
	v_rcp_f32_e32 v220, v220
	v_rcp_f32_e32 v221, v221
	v_rcp_f32_e32 v222, v222
	v_rcp_f32_e32 v223, v223
	v_rcp_f32_e32 v224, v224
	v_rcp_f32_e32 v225, v225
	v_pk_fma_f32 v[210:211], v[210:211], v[228:229], v[230:231]
	v_pk_fma_f32 v[212:213], v[212:213], v[228:229], v[230:231]
	v_pk_fma_f32 v[214:215], v[214:215], v[228:229], v[230:231]
	v_pk_fma_f32 v[216:217], v[216:217], v[228:229], v[230:231]
	v_pk_fma_f32 v[218:219], v[218:219], v[228:229], v[230:231]
	v_pk_fma_f32 v[220:221], v[220:221], v[228:229], v[230:231]
	v_pk_fma_f32 v[222:223], v[222:223], v[228:229], v[230:231]
	v_pk_fma_f32 v[224:225], v[224:225], v[228:229], v[230:231]
	v_med3_f32 v210, v210, 1.0, v182
	v_med3_f32 v211, v211, 1.0, v182
	v_med3_f32 v212, v212, 1.0, v182
	v_med3_f32 v213, v213, 1.0, v182
	v_med3_f32 v214, v214, 1.0, v182
	v_med3_f32 v215, v215, 1.0, v182
	v_med3_f32 v216, v216, 1.0, v182
	v_med3_f32 v217, v217, 1.0, v182
	v_med3_f32 v218, v218, 1.0, v182
	v_med3_f32 v219, v219, 1.0, v182
	v_med3_f32 v220, v220, 1.0, v182
	v_med3_f32 v221, v221, 1.0, v182
	v_med3_f32 v222, v222, 1.0, v182
	v_med3_f32 v223, v223, 1.0, v182
	v_med3_f32 v224, v224, 1.0, v182
	v_med3_f32 v225, v225, 1.0, v182
	v_cvt_u32_f32_e32 v210, v210
	v_cvt_u32_f32_e32 v211, v211
	v_cvt_u32_f32_sdwa v212, v212 dst_sel:WORD_1 dst_unused:UNUSED_PAD src0_sel:DWORD
	v_cvt_u32_f32_sdwa v213, v213 dst_sel:BYTE_3 dst_unused:UNUSED_PAD src0_sel:DWORD
	v_cvt_u32_f32_e32 v214, v214
	v_cvt_u32_f32_e32 v215, v215
	v_cvt_u32_f32_sdwa v216, v216 dst_sel:WORD_1 dst_unused:UNUSED_PAD src0_sel:DWORD
	v_cvt_u32_f32_sdwa v217, v217 dst_sel:BYTE_3 dst_unused:UNUSED_PAD src0_sel:DWORD
	v_cvt_u32_f32_e32 v218, v218
	v_cvt_u32_f32_e32 v219, v219
	v_cvt_u32_f32_sdwa v220, v220 dst_sel:WORD_1 dst_unused:UNUSED_PAD src0_sel:DWORD
	v_cvt_u32_f32_sdwa v221, v221 dst_sel:BYTE_3 dst_unused:UNUSED_PAD src0_sel:DWORD
	v_cvt_u32_f32_e32 v222, v222
	v_cvt_u32_f32_e32 v223, v223
	v_cvt_u32_f32_sdwa v224, v224 dst_sel:WORD_1 dst_unused:UNUSED_PAD src0_sel:DWORD
	v_cvt_u32_f32_sdwa v225, v225 dst_sel:BYTE_3 dst_unused:UNUSED_PAD src0_sel:DWORD
	v_lshl_or_b32 v210, v211, 8, v210
	v_lshl_or_b32 v214, v215, 8, v214
	v_lshl_or_b32 v218, v219, 8, v218
	v_lshl_or_b32 v222, v223, 8, v222
	v_or3_b32 v236, v210, v212, v213
	v_or3_b32 v237, v214, v216, v217
	v_or3_b32 v238, v218, v220, v221
	v_or3_b32 v239, v222, v224, v225
	v_add_co_u32_e32 v146, vcc, 0x8000, v148
	s_nop 1
	v_addc_co_u32_e32 v147, vcc, 0, v149, vcc
	global_store_dwordx4 v[146:147], v[236:239], off nt
	s_waitcnt vmcnt(7)
	v_mul_f32_e32 v130, 0xbfb8aa3b, v204
	v_pk_fma_f32 v[210:211], v[92:93], v[130:131], v[186:187] op_sel_hi:[1,0,1]
	v_pk_fma_f32 v[212:213], v[94:95], v[130:131], v[188:189] op_sel_hi:[1,0,1]
	v_pk_fma_f32 v[214:215], v[88:89], v[130:131], v[190:191] op_sel_hi:[1,0,1]
	v_pk_fma_f32 v[216:217], v[90:91], v[130:131], v[192:193] op_sel_hi:[1,0,1]
	v_pk_fma_f32 v[218:219], v[84:85], v[130:131], v[194:195] op_sel_hi:[1,0,1]
	v_pk_fma_f32 v[220:221], v[86:87], v[130:131], v[196:197] op_sel_hi:[1,0,1]
	v_pk_fma_f32 v[222:223], v[80:81], v[130:131], v[198:199] op_sel_hi:[1,0,1]
	v_pk_fma_f32 v[224:225], v[82:83], v[130:131], v[200:201] op_sel_hi:[1,0,1]
	v_exp_f32_e32 v210, v210
	v_exp_f32_e32 v211, v211
	v_exp_f32_e32 v212, v212
	v_exp_f32_e32 v213, v213
	v_exp_f32_e32 v214, v214
	v_exp_f32_e32 v215, v215
	v_exp_f32_e32 v216, v216
	v_exp_f32_e32 v217, v217
	v_exp_f32_e32 v218, v218
	v_exp_f32_e32 v219, v219
	v_exp_f32_e32 v220, v220
	v_exp_f32_e32 v221, v221
	v_exp_f32_e32 v222, v222
	v_exp_f32_e32 v223, v223
	v_exp_f32_e32 v224, v224
	v_exp_f32_e32 v225, v225
	v_pk_add_f32 v[210:211], v[210:211], v[226:227]
	v_pk_add_f32 v[212:213], v[212:213], v[226:227]
	v_pk_add_f32 v[214:215], v[214:215], v[226:227]
	v_pk_add_f32 v[216:217], v[216:217], v[226:227]
	v_pk_add_f32 v[218:219], v[218:219], v[226:227]
	v_pk_add_f32 v[220:221], v[220:221], v[226:227]
	v_pk_add_f32 v[222:223], v[222:223], v[226:227]
	v_pk_add_f32 v[224:225], v[224:225], v[226:227]
	v_rcp_f32_e32 v210, v210
	v_rcp_f32_e32 v211, v211
	v_rcp_f32_e32 v212, v212
	v_rcp_f32_e32 v213, v213
	v_rcp_f32_e32 v214, v214
	v_rcp_f32_e32 v215, v215
	v_rcp_f32_e32 v216, v216
	v_rcp_f32_e32 v217, v217
	v_rcp_f32_e32 v218, v218
	v_rcp_f32_e32 v219, v219
	v_rcp_f32_e32 v220, v220
	v_rcp_f32_e32 v221, v221
	v_rcp_f32_e32 v222, v222
	v_rcp_f32_e32 v223, v223
	v_rcp_f32_e32 v224, v224
	v_rcp_f32_e32 v225, v225
	v_pk_fma_f32 v[210:211], v[210:211], v[228:229], v[230:231]
	v_pk_fma_f32 v[212:213], v[212:213], v[228:229], v[230:231]
	v_pk_fma_f32 v[214:215], v[214:215], v[228:229], v[230:231]
	v_pk_fma_f32 v[216:217], v[216:217], v[228:229], v[230:231]
	v_pk_fma_f32 v[218:219], v[218:219], v[228:229], v[230:231]
	v_pk_fma_f32 v[220:221], v[220:221], v[228:229], v[230:231]
	v_pk_fma_f32 v[222:223], v[222:223], v[228:229], v[230:231]
	v_pk_fma_f32 v[224:225], v[224:225], v[228:229], v[230:231]
	v_med3_f32 v210, v210, 1.0, v182
	v_med3_f32 v211, v211, 1.0, v182
	v_med3_f32 v212, v212, 1.0, v182
	v_med3_f32 v213, v213, 1.0, v182
	v_med3_f32 v214, v214, 1.0, v182
	v_med3_f32 v215, v215, 1.0, v182
	v_med3_f32 v216, v216, 1.0, v182
	v_med3_f32 v217, v217, 1.0, v182
	v_med3_f32 v218, v218, 1.0, v182
	v_med3_f32 v219, v219, 1.0, v182
	v_med3_f32 v220, v220, 1.0, v182
	v_med3_f32 v221, v221, 1.0, v182
	v_med3_f32 v222, v222, 1.0, v182
	v_med3_f32 v223, v223, 1.0, v182
	v_med3_f32 v224, v224, 1.0, v182
	v_med3_f32 v225, v225, 1.0, v182
	v_cvt_u32_f32_e32 v210, v210
	v_cvt_u32_f32_e32 v211, v211
	v_cvt_u32_f32_sdwa v212, v212 dst_sel:WORD_1 dst_unused:UNUSED_PAD src0_sel:DWORD
	v_cvt_u32_f32_sdwa v213, v213 dst_sel:BYTE_3 dst_unused:UNUSED_PAD src0_sel:DWORD
	v_cvt_u32_f32_e32 v214, v214
	v_cvt_u32_f32_e32 v215, v215
	v_cvt_u32_f32_sdwa v216, v216 dst_sel:WORD_1 dst_unused:UNUSED_PAD src0_sel:DWORD
	v_cvt_u32_f32_sdwa v217, v217 dst_sel:BYTE_3 dst_unused:UNUSED_PAD src0_sel:DWORD
	v_cvt_u32_f32_e32 v218, v218
	v_cvt_u32_f32_e32 v219, v219
	v_cvt_u32_f32_sdwa v220, v220 dst_sel:WORD_1 dst_unused:UNUSED_PAD src0_sel:DWORD
	v_cvt_u32_f32_sdwa v221, v221 dst_sel:BYTE_3 dst_unused:UNUSED_PAD src0_sel:DWORD
	v_cvt_u32_f32_e32 v222, v222
	v_cvt_u32_f32_e32 v223, v223
	v_cvt_u32_f32_sdwa v224, v224 dst_sel:WORD_1 dst_unused:UNUSED_PAD src0_sel:DWORD
	v_cvt_u32_f32_sdwa v225, v225 dst_sel:BYTE_3 dst_unused:UNUSED_PAD src0_sel:DWORD
	v_lshl_or_b32 v210, v211, 8, v210
	v_lshl_or_b32 v214, v215, 8, v214
	v_lshl_or_b32 v218, v219, 8, v218
	v_lshl_or_b32 v222, v223, 8, v222
	v_or3_b32 v236, v210, v212, v213
	v_or3_b32 v237, v214, v216, v217
	v_or3_b32 v238, v218, v220, v221
	v_or3_b32 v239, v222, v224, v225
	v_add_co_u32_e32 v146, vcc, 0x10000, v148
	s_nop 1
	v_addc_co_u32_e32 v147, vcc, 0, v149, vcc
	global_store_dwordx4 v[146:147], v[236:239], off nt
	s_waitcnt vmcnt(7)
	v_mul_f32_e32 v130, 0xbfb8aa3b, v205
	v_pk_fma_f32 v[210:211], v[76:77], v[130:131], v[186:187] op_sel_hi:[1,0,1]
	v_pk_fma_f32 v[212:213], v[78:79], v[130:131], v[188:189] op_sel_hi:[1,0,1]
	v_pk_fma_f32 v[214:215], v[72:73], v[130:131], v[190:191] op_sel_hi:[1,0,1]
	v_pk_fma_f32 v[216:217], v[74:75], v[130:131], v[192:193] op_sel_hi:[1,0,1]
	v_pk_fma_f32 v[218:219], v[68:69], v[130:131], v[194:195] op_sel_hi:[1,0,1]
	v_pk_fma_f32 v[220:221], v[70:71], v[130:131], v[196:197] op_sel_hi:[1,0,1]
	v_pk_fma_f32 v[222:223], v[64:65], v[130:131], v[198:199] op_sel_hi:[1,0,1]
	v_pk_fma_f32 v[224:225], v[66:67], v[130:131], v[200:201] op_sel_hi:[1,0,1]
	v_exp_f32_e32 v210, v210
	v_exp_f32_e32 v211, v211
	v_exp_f32_e32 v212, v212
	v_exp_f32_e32 v213, v213
	v_exp_f32_e32 v214, v214
	v_exp_f32_e32 v215, v215
	v_exp_f32_e32 v216, v216
	v_exp_f32_e32 v217, v217
	v_exp_f32_e32 v218, v218
	v_exp_f32_e32 v219, v219
	v_exp_f32_e32 v220, v220
	v_exp_f32_e32 v221, v221
	v_exp_f32_e32 v222, v222
	v_exp_f32_e32 v223, v223
	v_exp_f32_e32 v224, v224
	v_exp_f32_e32 v225, v225
	v_pk_add_f32 v[210:211], v[210:211], v[226:227]
	v_pk_add_f32 v[212:213], v[212:213], v[226:227]
	v_pk_add_f32 v[214:215], v[214:215], v[226:227]
	v_pk_add_f32 v[216:217], v[216:217], v[226:227]
	v_pk_add_f32 v[218:219], v[218:219], v[226:227]
	v_pk_add_f32 v[220:221], v[220:221], v[226:227]
	v_pk_add_f32 v[222:223], v[222:223], v[226:227]
	v_pk_add_f32 v[224:225], v[224:225], v[226:227]
	v_rcp_f32_e32 v210, v210
	v_rcp_f32_e32 v211, v211
	v_rcp_f32_e32 v212, v212
	v_rcp_f32_e32 v213, v213
	v_rcp_f32_e32 v214, v214
	v_rcp_f32_e32 v215, v215
	v_rcp_f32_e32 v216, v216
	v_rcp_f32_e32 v217, v217
	v_rcp_f32_e32 v218, v218
	v_rcp_f32_e32 v219, v219
	v_rcp_f32_e32 v220, v220
	v_rcp_f32_e32 v221, v221
	v_rcp_f32_e32 v222, v222
	v_rcp_f32_e32 v223, v223
	v_rcp_f32_e32 v224, v224
	v_rcp_f32_e32 v225, v225
	v_pk_fma_f32 v[210:211], v[210:211], v[228:229], v[230:231]
	v_pk_fma_f32 v[212:213], v[212:213], v[228:229], v[230:231]
	v_pk_fma_f32 v[214:215], v[214:215], v[228:229], v[230:231]
	v_pk_fma_f32 v[216:217], v[216:217], v[228:229], v[230:231]
	v_pk_fma_f32 v[218:219], v[218:219], v[228:229], v[230:231]
	v_pk_fma_f32 v[220:221], v[220:221], v[228:229], v[230:231]
	v_pk_fma_f32 v[222:223], v[222:223], v[228:229], v[230:231]
	v_pk_fma_f32 v[224:225], v[224:225], v[228:229], v[230:231]
	v_med3_f32 v210, v210, 1.0, v182
	v_med3_f32 v211, v211, 1.0, v182
	v_med3_f32 v212, v212, 1.0, v182
	v_med3_f32 v213, v213, 1.0, v182
	v_med3_f32 v214, v214, 1.0, v182
	v_med3_f32 v215, v215, 1.0, v182
	v_med3_f32 v216, v216, 1.0, v182
	v_med3_f32 v217, v217, 1.0, v182
	v_med3_f32 v218, v218, 1.0, v182
	v_med3_f32 v219, v219, 1.0, v182
	v_med3_f32 v220, v220, 1.0, v182
	v_med3_f32 v221, v221, 1.0, v182
	v_med3_f32 v222, v222, 1.0, v182
	v_med3_f32 v223, v223, 1.0, v182
	v_med3_f32 v224, v224, 1.0, v182
	v_med3_f32 v225, v225, 1.0, v182
	v_cvt_u32_f32_e32 v210, v210
	v_cvt_u32_f32_e32 v211, v211
	v_cvt_u32_f32_sdwa v212, v212 dst_sel:WORD_1 dst_unused:UNUSED_PAD src0_sel:DWORD
	v_cvt_u32_f32_sdwa v213, v213 dst_sel:BYTE_3 dst_unused:UNUSED_PAD src0_sel:DWORD
	v_cvt_u32_f32_e32 v214, v214
	v_cvt_u32_f32_e32 v215, v215
	v_cvt_u32_f32_sdwa v216, v216 dst_sel:WORD_1 dst_unused:UNUSED_PAD src0_sel:DWORD
	v_cvt_u32_f32_sdwa v217, v217 dst_sel:BYTE_3 dst_unused:UNUSED_PAD src0_sel:DWORD
	v_cvt_u32_f32_e32 v218, v218
	v_cvt_u32_f32_e32 v219, v219
	v_cvt_u32_f32_sdwa v220, v220 dst_sel:WORD_1 dst_unused:UNUSED_PAD src0_sel:DWORD
	v_cvt_u32_f32_sdwa v221, v221 dst_sel:BYTE_3 dst_unused:UNUSED_PAD src0_sel:DWORD
	v_cvt_u32_f32_e32 v222, v222
	v_cvt_u32_f32_e32 v223, v223
	v_cvt_u32_f32_sdwa v224, v224 dst_sel:WORD_1 dst_unused:UNUSED_PAD src0_sel:DWORD
	v_cvt_u32_f32_sdwa v225, v225 dst_sel:BYTE_3 dst_unused:UNUSED_PAD src0_sel:DWORD
	v_lshl_or_b32 v210, v211, 8, v210
	v_lshl_or_b32 v214, v215, 8, v214
	v_lshl_or_b32 v218, v219, 8, v218
	v_lshl_or_b32 v222, v223, 8, v222
	v_or3_b32 v236, v210, v212, v213
	v_or3_b32 v237, v214, v216, v217
	v_or3_b32 v238, v218, v220, v221
	v_or3_b32 v239, v222, v224, v225
	v_add_co_u32_e32 v146, vcc, 0x18000, v148
	s_nop 1
	v_addc_co_u32_e32 v147, vcc, 0, v149, vcc
	global_store_dwordx4 v[146:147], v[236:239], off nt
	s_waitcnt vmcnt(7)
	v_mul_f32_e32 v130, 0xbfb8aa3b, v206
	v_pk_fma_f32 v[210:211], v[60:61], v[130:131], v[186:187] op_sel_hi:[1,0,1]
	v_pk_fma_f32 v[212:213], v[62:63], v[130:131], v[188:189] op_sel_hi:[1,0,1]
	v_pk_fma_f32 v[214:215], v[56:57], v[130:131], v[190:191] op_sel_hi:[1,0,1]
	v_pk_fma_f32 v[216:217], v[58:59], v[130:131], v[192:193] op_sel_hi:[1,0,1]
	v_pk_fma_f32 v[218:219], v[52:53], v[130:131], v[194:195] op_sel_hi:[1,0,1]
	v_pk_fma_f32 v[220:221], v[54:55], v[130:131], v[196:197] op_sel_hi:[1,0,1]
	v_pk_fma_f32 v[222:223], v[48:49], v[130:131], v[198:199] op_sel_hi:[1,0,1]
	v_pk_fma_f32 v[224:225], v[50:51], v[130:131], v[200:201] op_sel_hi:[1,0,1]
	v_exp_f32_e32 v210, v210
	v_exp_f32_e32 v211, v211
	v_exp_f32_e32 v212, v212
	v_exp_f32_e32 v213, v213
	v_exp_f32_e32 v214, v214
	v_exp_f32_e32 v215, v215
	v_exp_f32_e32 v216, v216
	v_exp_f32_e32 v217, v217
	v_exp_f32_e32 v218, v218
	v_exp_f32_e32 v219, v219
	v_exp_f32_e32 v220, v220
	v_exp_f32_e32 v221, v221
	v_exp_f32_e32 v222, v222
	v_exp_f32_e32 v223, v223
	v_exp_f32_e32 v224, v224
	v_exp_f32_e32 v225, v225
	v_pk_add_f32 v[210:211], v[210:211], v[226:227]
	v_pk_add_f32 v[212:213], v[212:213], v[226:227]
	v_pk_add_f32 v[214:215], v[214:215], v[226:227]
	v_pk_add_f32 v[216:217], v[216:217], v[226:227]
	v_pk_add_f32 v[218:219], v[218:219], v[226:227]
	v_pk_add_f32 v[220:221], v[220:221], v[226:227]
	v_pk_add_f32 v[222:223], v[222:223], v[226:227]
	v_pk_add_f32 v[224:225], v[224:225], v[226:227]
	v_rcp_f32_e32 v210, v210
	v_rcp_f32_e32 v211, v211
	v_rcp_f32_e32 v212, v212
	v_rcp_f32_e32 v213, v213
	v_rcp_f32_e32 v214, v214
	v_rcp_f32_e32 v215, v215
	v_rcp_f32_e32 v216, v216
	v_rcp_f32_e32 v217, v217
	v_rcp_f32_e32 v218, v218
	v_rcp_f32_e32 v219, v219
	v_rcp_f32_e32 v220, v220
	v_rcp_f32_e32 v221, v221
	v_rcp_f32_e32 v222, v222
	v_rcp_f32_e32 v223, v223
	v_rcp_f32_e32 v224, v224
	v_rcp_f32_e32 v225, v225
	v_pk_fma_f32 v[210:211], v[210:211], v[228:229], v[230:231]
	v_pk_fma_f32 v[212:213], v[212:213], v[228:229], v[230:231]
	v_pk_fma_f32 v[214:215], v[214:215], v[228:229], v[230:231]
	v_pk_fma_f32 v[216:217], v[216:217], v[228:229], v[230:231]
	v_pk_fma_f32 v[218:219], v[218:219], v[228:229], v[230:231]
	v_pk_fma_f32 v[220:221], v[220:221], v[228:229], v[230:231]
	v_pk_fma_f32 v[222:223], v[222:223], v[228:229], v[230:231]
	v_pk_fma_f32 v[224:225], v[224:225], v[228:229], v[230:231]
	v_med3_f32 v210, v210, 1.0, v182
	v_med3_f32 v211, v211, 1.0, v182
	v_med3_f32 v212, v212, 1.0, v182
	v_med3_f32 v213, v213, 1.0, v182
	v_med3_f32 v214, v214, 1.0, v182
	v_med3_f32 v215, v215, 1.0, v182
	v_med3_f32 v216, v216, 1.0, v182
	v_med3_f32 v217, v217, 1.0, v182
	v_med3_f32 v218, v218, 1.0, v182
	v_med3_f32 v219, v219, 1.0, v182
	v_med3_f32 v220, v220, 1.0, v182
	v_med3_f32 v221, v221, 1.0, v182
	v_med3_f32 v222, v222, 1.0, v182
	v_med3_f32 v223, v223, 1.0, v182
	v_med3_f32 v224, v224, 1.0, v182
	v_med3_f32 v225, v225, 1.0, v182
	v_cvt_u32_f32_e32 v210, v210
	v_cvt_u32_f32_e32 v211, v211
	v_cvt_u32_f32_sdwa v212, v212 dst_sel:WORD_1 dst_unused:UNUSED_PAD src0_sel:DWORD
	v_cvt_u32_f32_sdwa v213, v213 dst_sel:BYTE_3 dst_unused:UNUSED_PAD src0_sel:DWORD
	v_cvt_u32_f32_e32 v214, v214
	v_cvt_u32_f32_e32 v215, v215
	v_cvt_u32_f32_sdwa v216, v216 dst_sel:WORD_1 dst_unused:UNUSED_PAD src0_sel:DWORD
	v_cvt_u32_f32_sdwa v217, v217 dst_sel:BYTE_3 dst_unused:UNUSED_PAD src0_sel:DWORD
	v_cvt_u32_f32_e32 v218, v218
	v_cvt_u32_f32_e32 v219, v219
	v_cvt_u32_f32_sdwa v220, v220 dst_sel:WORD_1 dst_unused:UNUSED_PAD src0_sel:DWORD
	v_cvt_u32_f32_sdwa v221, v221 dst_sel:BYTE_3 dst_unused:UNUSED_PAD src0_sel:DWORD
	v_cvt_u32_f32_e32 v222, v222
	v_cvt_u32_f32_e32 v223, v223
	v_cvt_u32_f32_sdwa v224, v224 dst_sel:WORD_1 dst_unused:UNUSED_PAD src0_sel:DWORD
	v_cvt_u32_f32_sdwa v225, v225 dst_sel:BYTE_3 dst_unused:UNUSED_PAD src0_sel:DWORD
	v_lshl_or_b32 v210, v211, 8, v210
	v_lshl_or_b32 v214, v215, 8, v214
	v_lshl_or_b32 v218, v219, 8, v218
	v_lshl_or_b32 v222, v223, 8, v222
	v_or3_b32 v236, v210, v212, v213
	v_or3_b32 v237, v214, v216, v217
	v_or3_b32 v238, v218, v220, v221
	v_or3_b32 v239, v222, v224, v225
	v_add_co_u32_e32 v146, vcc, 0x40000, v148
	s_nop 1
	v_addc_co_u32_e32 v147, vcc, 0, v149, vcc
	global_store_dwordx4 v[146:147], v[236:239], off nt
	s_waitcnt vmcnt(7)
	v_mul_f32_e32 v130, 0xbfb8aa3b, v207
	v_pk_fma_f32 v[210:211], v[44:45], v[130:131], v[186:187] op_sel_hi:[1,0,1]
	v_pk_fma_f32 v[212:213], v[46:47], v[130:131], v[188:189] op_sel_hi:[1,0,1]
	v_pk_fma_f32 v[214:215], v[40:41], v[130:131], v[190:191] op_sel_hi:[1,0,1]
	v_pk_fma_f32 v[216:217], v[42:43], v[130:131], v[192:193] op_sel_hi:[1,0,1]
	v_pk_fma_f32 v[218:219], v[36:37], v[130:131], v[194:195] op_sel_hi:[1,0,1]
	v_pk_fma_f32 v[220:221], v[38:39], v[130:131], v[196:197] op_sel_hi:[1,0,1]
	v_pk_fma_f32 v[222:223], v[32:33], v[130:131], v[198:199] op_sel_hi:[1,0,1]
	v_pk_fma_f32 v[224:225], v[34:35], v[130:131], v[200:201] op_sel_hi:[1,0,1]
	v_exp_f32_e32 v210, v210
	v_exp_f32_e32 v211, v211
	v_exp_f32_e32 v212, v212
	v_exp_f32_e32 v213, v213
	v_exp_f32_e32 v214, v214
	v_exp_f32_e32 v215, v215
	v_exp_f32_e32 v216, v216
	v_exp_f32_e32 v217, v217
	v_exp_f32_e32 v218, v218
	v_exp_f32_e32 v219, v219
	v_exp_f32_e32 v220, v220
	v_exp_f32_e32 v221, v221
	v_exp_f32_e32 v222, v222
	v_exp_f32_e32 v223, v223
	v_exp_f32_e32 v224, v224
	v_exp_f32_e32 v225, v225
	v_pk_add_f32 v[210:211], v[210:211], v[226:227]
	v_pk_add_f32 v[212:213], v[212:213], v[226:227]
	v_pk_add_f32 v[214:215], v[214:215], v[226:227]
	v_pk_add_f32 v[216:217], v[216:217], v[226:227]
	v_pk_add_f32 v[218:219], v[218:219], v[226:227]
	v_pk_add_f32 v[220:221], v[220:221], v[226:227]
	v_pk_add_f32 v[222:223], v[222:223], v[226:227]
	v_pk_add_f32 v[224:225], v[224:225], v[226:227]
	v_rcp_f32_e32 v210, v210
	v_rcp_f32_e32 v211, v211
	v_rcp_f32_e32 v212, v212
	v_rcp_f32_e32 v213, v213
	v_rcp_f32_e32 v214, v214
	v_rcp_f32_e32 v215, v215
	v_rcp_f32_e32 v216, v216
	v_rcp_f32_e32 v217, v217
	v_rcp_f32_e32 v218, v218
	v_rcp_f32_e32 v219, v219
	v_rcp_f32_e32 v220, v220
	v_rcp_f32_e32 v221, v221
	v_rcp_f32_e32 v222, v222
	v_rcp_f32_e32 v223, v223
	v_rcp_f32_e32 v224, v224
	v_rcp_f32_e32 v225, v225
	v_pk_fma_f32 v[210:211], v[210:211], v[228:229], v[230:231]
	v_pk_fma_f32 v[212:213], v[212:213], v[228:229], v[230:231]
	v_pk_fma_f32 v[214:215], v[214:215], v[228:229], v[230:231]
	v_pk_fma_f32 v[216:217], v[216:217], v[228:229], v[230:231]
	v_pk_fma_f32 v[218:219], v[218:219], v[228:229], v[230:231]
	v_pk_fma_f32 v[220:221], v[220:221], v[228:229], v[230:231]
	v_pk_fma_f32 v[222:223], v[222:223], v[228:229], v[230:231]
	v_pk_fma_f32 v[224:225], v[224:225], v[228:229], v[230:231]
	v_med3_f32 v210, v210, 1.0, v182
	v_med3_f32 v211, v211, 1.0, v182
	v_med3_f32 v212, v212, 1.0, v182
	v_med3_f32 v213, v213, 1.0, v182
	v_med3_f32 v214, v214, 1.0, v182
	v_med3_f32 v215, v215, 1.0, v182
	v_med3_f32 v216, v216, 1.0, v182
	v_med3_f32 v217, v217, 1.0, v182
	v_med3_f32 v218, v218, 1.0, v182
	v_med3_f32 v219, v219, 1.0, v182
	v_med3_f32 v220, v220, 1.0, v182
	v_med3_f32 v221, v221, 1.0, v182
	v_med3_f32 v222, v222, 1.0, v182
	v_med3_f32 v223, v223, 1.0, v182
	v_med3_f32 v224, v224, 1.0, v182
	v_med3_f32 v225, v225, 1.0, v182
	v_cvt_u32_f32_e32 v210, v210
	v_cvt_u32_f32_e32 v211, v211
	v_cvt_u32_f32_sdwa v212, v212 dst_sel:WORD_1 dst_unused:UNUSED_PAD src0_sel:DWORD
	v_cvt_u32_f32_sdwa v213, v213 dst_sel:BYTE_3 dst_unused:UNUSED_PAD src0_sel:DWORD
	v_cvt_u32_f32_e32 v214, v214
	v_cvt_u32_f32_e32 v215, v215
	v_cvt_u32_f32_sdwa v216, v216 dst_sel:WORD_1 dst_unused:UNUSED_PAD src0_sel:DWORD
	v_cvt_u32_f32_sdwa v217, v217 dst_sel:BYTE_3 dst_unused:UNUSED_PAD src0_sel:DWORD
	v_cvt_u32_f32_e32 v218, v218
	v_cvt_u32_f32_e32 v219, v219
	v_cvt_u32_f32_sdwa v220, v220 dst_sel:WORD_1 dst_unused:UNUSED_PAD src0_sel:DWORD
	v_cvt_u32_f32_sdwa v221, v221 dst_sel:BYTE_3 dst_unused:UNUSED_PAD src0_sel:DWORD
	v_cvt_u32_f32_e32 v222, v222
	v_cvt_u32_f32_e32 v223, v223
	v_cvt_u32_f32_sdwa v224, v224 dst_sel:WORD_1 dst_unused:UNUSED_PAD src0_sel:DWORD
	v_cvt_u32_f32_sdwa v225, v225 dst_sel:BYTE_3 dst_unused:UNUSED_PAD src0_sel:DWORD
	v_lshl_or_b32 v210, v211, 8, v210
	v_lshl_or_b32 v214, v215, 8, v214
	v_lshl_or_b32 v218, v219, 8, v218
	v_lshl_or_b32 v222, v223, 8, v222
	v_or3_b32 v236, v210, v212, v213
	v_or3_b32 v237, v214, v216, v217
	v_or3_b32 v238, v218, v220, v221
	v_or3_b32 v239, v222, v224, v225
	v_add_co_u32_e32 v146, vcc, 0x48000, v148
	s_nop 1
	v_addc_co_u32_e32 v147, vcc, 0, v149, vcc
	global_store_dwordx4 v[146:147], v[236:239], off nt
	s_waitcnt vmcnt(7)
	v_mul_f32_e32 v130, 0xbfb8aa3b, v208
	v_pk_fma_f32 v[210:211], v[28:29], v[130:131], v[186:187] op_sel_hi:[1,0,1]
	v_pk_fma_f32 v[212:213], v[30:31], v[130:131], v[188:189] op_sel_hi:[1,0,1]
	v_pk_fma_f32 v[214:215], v[24:25], v[130:131], v[190:191] op_sel_hi:[1,0,1]
	v_pk_fma_f32 v[216:217], v[26:27], v[130:131], v[192:193] op_sel_hi:[1,0,1]
	v_pk_fma_f32 v[218:219], v[20:21], v[130:131], v[194:195] op_sel_hi:[1,0,1]
	v_pk_fma_f32 v[220:221], v[22:23], v[130:131], v[196:197] op_sel_hi:[1,0,1]
	v_pk_fma_f32 v[222:223], v[16:17], v[130:131], v[198:199] op_sel_hi:[1,0,1]
	v_pk_fma_f32 v[224:225], v[18:19], v[130:131], v[200:201] op_sel_hi:[1,0,1]
	v_exp_f32_e32 v210, v210
	v_exp_f32_e32 v211, v211
	v_exp_f32_e32 v212, v212
	v_exp_f32_e32 v213, v213
	v_exp_f32_e32 v214, v214
	v_exp_f32_e32 v215, v215
	v_exp_f32_e32 v216, v216
	v_exp_f32_e32 v217, v217
	v_exp_f32_e32 v218, v218
	v_exp_f32_e32 v219, v219
	v_exp_f32_e32 v220, v220
	v_exp_f32_e32 v221, v221
	v_exp_f32_e32 v222, v222
	v_exp_f32_e32 v223, v223
	v_exp_f32_e32 v224, v224
	v_exp_f32_e32 v225, v225
	v_pk_add_f32 v[210:211], v[210:211], v[226:227]
	v_pk_add_f32 v[212:213], v[212:213], v[226:227]
	v_pk_add_f32 v[214:215], v[214:215], v[226:227]
	v_pk_add_f32 v[216:217], v[216:217], v[226:227]
	v_pk_add_f32 v[218:219], v[218:219], v[226:227]
	v_pk_add_f32 v[220:221], v[220:221], v[226:227]
	v_pk_add_f32 v[222:223], v[222:223], v[226:227]
	v_pk_add_f32 v[224:225], v[224:225], v[226:227]
	v_rcp_f32_e32 v210, v210
	v_rcp_f32_e32 v211, v211
	v_rcp_f32_e32 v212, v212
	v_rcp_f32_e32 v213, v213
	v_rcp_f32_e32 v214, v214
	v_rcp_f32_e32 v215, v215
	v_rcp_f32_e32 v216, v216
	v_rcp_f32_e32 v217, v217
	v_rcp_f32_e32 v218, v218
	v_rcp_f32_e32 v219, v219
	v_rcp_f32_e32 v220, v220
	v_rcp_f32_e32 v221, v221
	v_rcp_f32_e32 v222, v222
	v_rcp_f32_e32 v223, v223
	v_rcp_f32_e32 v224, v224
	v_rcp_f32_e32 v225, v225
	v_pk_fma_f32 v[210:211], v[210:211], v[228:229], v[230:231]
	v_pk_fma_f32 v[212:213], v[212:213], v[228:229], v[230:231]
	v_pk_fma_f32 v[214:215], v[214:215], v[228:229], v[230:231]
	v_pk_fma_f32 v[216:217], v[216:217], v[228:229], v[230:231]
	v_pk_fma_f32 v[218:219], v[218:219], v[228:229], v[230:231]
	v_pk_fma_f32 v[220:221], v[220:221], v[228:229], v[230:231]
	v_pk_fma_f32 v[222:223], v[222:223], v[228:229], v[230:231]
	v_pk_fma_f32 v[224:225], v[224:225], v[228:229], v[230:231]
	v_med3_f32 v210, v210, 1.0, v182
	v_med3_f32 v211, v211, 1.0, v182
	v_med3_f32 v212, v212, 1.0, v182
	v_med3_f32 v213, v213, 1.0, v182
	v_med3_f32 v214, v214, 1.0, v182
	v_med3_f32 v215, v215, 1.0, v182
	v_med3_f32 v216, v216, 1.0, v182
	v_med3_f32 v217, v217, 1.0, v182
	v_med3_f32 v218, v218, 1.0, v182
	v_med3_f32 v219, v219, 1.0, v182
	v_med3_f32 v220, v220, 1.0, v182
	v_med3_f32 v221, v221, 1.0, v182
	v_med3_f32 v222, v222, 1.0, v182
	v_med3_f32 v223, v223, 1.0, v182
	v_med3_f32 v224, v224, 1.0, v182
	v_med3_f32 v225, v225, 1.0, v182
	v_cvt_u32_f32_e32 v210, v210
	v_cvt_u32_f32_e32 v211, v211
	v_cvt_u32_f32_sdwa v212, v212 dst_sel:WORD_1 dst_unused:UNUSED_PAD src0_sel:DWORD
	v_cvt_u32_f32_sdwa v213, v213 dst_sel:BYTE_3 dst_unused:UNUSED_PAD src0_sel:DWORD
	v_cvt_u32_f32_e32 v214, v214
	v_cvt_u32_f32_e32 v215, v215
	v_cvt_u32_f32_sdwa v216, v216 dst_sel:WORD_1 dst_unused:UNUSED_PAD src0_sel:DWORD
	v_cvt_u32_f32_sdwa v217, v217 dst_sel:BYTE_3 dst_unused:UNUSED_PAD src0_sel:DWORD
	v_cvt_u32_f32_e32 v218, v218
	v_cvt_u32_f32_e32 v219, v219
	v_cvt_u32_f32_sdwa v220, v220 dst_sel:WORD_1 dst_unused:UNUSED_PAD src0_sel:DWORD
	v_cvt_u32_f32_sdwa v221, v221 dst_sel:BYTE_3 dst_unused:UNUSED_PAD src0_sel:DWORD
	v_cvt_u32_f32_e32 v222, v222
	v_cvt_u32_f32_e32 v223, v223
	v_cvt_u32_f32_sdwa v224, v224 dst_sel:WORD_1 dst_unused:UNUSED_PAD src0_sel:DWORD
	v_cvt_u32_f32_sdwa v225, v225 dst_sel:BYTE_3 dst_unused:UNUSED_PAD src0_sel:DWORD
	v_lshl_or_b32 v210, v211, 8, v210
	v_lshl_or_b32 v214, v215, 8, v214
	v_lshl_or_b32 v218, v219, 8, v218
	v_lshl_or_b32 v222, v223, 8, v222
	v_or3_b32 v236, v210, v212, v213
	v_or3_b32 v237, v214, v216, v217
	v_or3_b32 v238, v218, v220, v221
	v_or3_b32 v239, v222, v224, v225
	v_add_co_u32_e32 v146, vcc, 0x50000, v148
	s_nop 1
	v_addc_co_u32_e32 v147, vcc, 0, v149, vcc
	global_store_dwordx4 v[146:147], v[236:239], off nt
	s_waitcnt vmcnt(7)
	v_mul_f32_e32 v130, 0xbfb8aa3b, v209
	v_pk_fma_f32 v[210:211], v[12:13], v[130:131], v[186:187] op_sel_hi:[1,0,1]
	v_pk_fma_f32 v[212:213], v[14:15], v[130:131], v[188:189] op_sel_hi:[1,0,1]
	v_pk_fma_f32 v[214:215], v[8:9], v[130:131], v[190:191] op_sel_hi:[1,0,1]
	v_pk_fma_f32 v[216:217], v[10:11], v[130:131], v[192:193] op_sel_hi:[1,0,1]
	v_pk_fma_f32 v[218:219], v[4:5], v[130:131], v[194:195] op_sel_hi:[1,0,1]
	v_pk_fma_f32 v[220:221], v[6:7], v[130:131], v[196:197] op_sel_hi:[1,0,1]
	v_pk_fma_f32 v[222:223], v[0:1], v[130:131], v[198:199] op_sel_hi:[1,0,1]
	v_pk_fma_f32 v[224:225], v[2:3], v[130:131], v[200:201] op_sel_hi:[1,0,1]
	v_exp_f32_e32 v210, v210
	v_exp_f32_e32 v211, v211
	v_exp_f32_e32 v212, v212
	v_exp_f32_e32 v213, v213
	v_exp_f32_e32 v214, v214
	v_exp_f32_e32 v215, v215
	v_exp_f32_e32 v216, v216
	v_exp_f32_e32 v217, v217
	v_exp_f32_e32 v218, v218
	v_exp_f32_e32 v219, v219
	v_exp_f32_e32 v220, v220
	v_exp_f32_e32 v221, v221
	v_exp_f32_e32 v222, v222
	v_exp_f32_e32 v223, v223
	v_exp_f32_e32 v224, v224
	v_exp_f32_e32 v225, v225
	v_pk_add_f32 v[210:211], v[210:211], v[226:227]
	v_pk_add_f32 v[212:213], v[212:213], v[226:227]
	v_pk_add_f32 v[214:215], v[214:215], v[226:227]
	v_pk_add_f32 v[216:217], v[216:217], v[226:227]
	v_pk_add_f32 v[218:219], v[218:219], v[226:227]
	v_pk_add_f32 v[220:221], v[220:221], v[226:227]
	v_pk_add_f32 v[222:223], v[222:223], v[226:227]
	v_pk_add_f32 v[224:225], v[224:225], v[226:227]
	v_rcp_f32_e32 v210, v210
	v_rcp_f32_e32 v211, v211
	v_rcp_f32_e32 v212, v212
	v_rcp_f32_e32 v213, v213
	v_rcp_f32_e32 v214, v214
	v_rcp_f32_e32 v215, v215
	v_rcp_f32_e32 v216, v216
	v_rcp_f32_e32 v217, v217
	v_rcp_f32_e32 v218, v218
	v_rcp_f32_e32 v219, v219
	v_rcp_f32_e32 v220, v220
	v_rcp_f32_e32 v221, v221
	v_rcp_f32_e32 v222, v222
	v_rcp_f32_e32 v223, v223
	v_rcp_f32_e32 v224, v224
	v_rcp_f32_e32 v225, v225
	v_pk_fma_f32 v[210:211], v[210:211], v[228:229], v[230:231]
	v_pk_fma_f32 v[212:213], v[212:213], v[228:229], v[230:231]
	v_pk_fma_f32 v[214:215], v[214:215], v[228:229], v[230:231]
	v_pk_fma_f32 v[216:217], v[216:217], v[228:229], v[230:231]
	v_pk_fma_f32 v[218:219], v[218:219], v[228:229], v[230:231]
	v_pk_fma_f32 v[220:221], v[220:221], v[228:229], v[230:231]
	v_pk_fma_f32 v[222:223], v[222:223], v[228:229], v[230:231]
	v_pk_fma_f32 v[224:225], v[224:225], v[228:229], v[230:231]
	v_med3_f32 v210, v210, 1.0, v182
	v_med3_f32 v211, v211, 1.0, v182
	v_med3_f32 v212, v212, 1.0, v182
	v_med3_f32 v213, v213, 1.0, v182
	v_med3_f32 v214, v214, 1.0, v182
	v_med3_f32 v215, v215, 1.0, v182
	v_med3_f32 v216, v216, 1.0, v182
	v_med3_f32 v217, v217, 1.0, v182
	v_med3_f32 v218, v218, 1.0, v182
	v_med3_f32 v219, v219, 1.0, v182
	v_med3_f32 v220, v220, 1.0, v182
	v_med3_f32 v221, v221, 1.0, v182
	v_med3_f32 v222, v222, 1.0, v182
	v_med3_f32 v223, v223, 1.0, v182
	v_med3_f32 v224, v224, 1.0, v182
	v_med3_f32 v225, v225, 1.0, v182
	v_cvt_u32_f32_e32 v210, v210
	v_cvt_u32_f32_e32 v211, v211
	v_cvt_u32_f32_sdwa v212, v212 dst_sel:WORD_1 dst_unused:UNUSED_PAD src0_sel:DWORD
	v_cvt_u32_f32_sdwa v213, v213 dst_sel:BYTE_3 dst_unused:UNUSED_PAD src0_sel:DWORD
	v_cvt_u32_f32_e32 v214, v214
	v_cvt_u32_f32_e32 v215, v215
	v_cvt_u32_f32_sdwa v216, v216 dst_sel:WORD_1 dst_unused:UNUSED_PAD src0_sel:DWORD
	v_cvt_u32_f32_sdwa v217, v217 dst_sel:BYTE_3 dst_unused:UNUSED_PAD src0_sel:DWORD
	v_cvt_u32_f32_e32 v218, v218
	v_cvt_u32_f32_e32 v219, v219
	v_cvt_u32_f32_sdwa v220, v220 dst_sel:WORD_1 dst_unused:UNUSED_PAD src0_sel:DWORD
	v_cvt_u32_f32_sdwa v221, v221 dst_sel:BYTE_3 dst_unused:UNUSED_PAD src0_sel:DWORD
	v_cvt_u32_f32_e32 v222, v222
	v_cvt_u32_f32_e32 v223, v223
	v_cvt_u32_f32_sdwa v224, v224 dst_sel:WORD_1 dst_unused:UNUSED_PAD src0_sel:DWORD
	v_cvt_u32_f32_sdwa v225, v225 dst_sel:BYTE_3 dst_unused:UNUSED_PAD src0_sel:DWORD
	v_lshl_or_b32 v210, v211, 8, v210
	v_lshl_or_b32 v214, v215, 8, v214
	v_lshl_or_b32 v218, v219, 8, v218
	v_lshl_or_b32 v222, v223, 8, v222
	v_or3_b32 v236, v210, v212, v213
	v_or3_b32 v237, v214, v216, v217
	v_or3_b32 v238, v218, v220, v221
	v_or3_b32 v239, v222, v224, v225
	v_add_co_u32_e32 v146, vcc, 0x58000, v148
	s_nop 1
	v_addc_co_u32_e32 v147, vcc, 0, v149, vcc
	global_store_dwordx4 v[146:147], v[236:239], off nt
	s_mov_b32 s12, 0x40000
